# 4-phase k-loop (merged MFMA groups, saddr-form DMA stages) also for branch and out GEMM loops
# baseline (speedup 1.0000x reference)
.Lbr_nozero:
.LBB0_1203:
	s_add_u32 s4, s2, 0xfff80080
	s_addc_u32 s5, s3, -1
	s_add_i32 s23, 0, 0x10000
	v_add_u32_e32 v32, s23, v218
	ds_read_b128 v[66:69], v32
	ds_read_b128 v[70:73], v32 offset:1024
	ds_read_b128 v[82:85], v32 offset:2048
	ds_read_b128 v[86:89], v32 offset:3072
	s_cmp_eq_u32 s15, 28
	s_cselect_b32 s7, s17, s5
	s_cselect_b32 s6, s16, s4
	s_cselect_b32 s5, s19, s13
	s_cselect_b32 s4, s18, s9
	s_add_i32 s26, 0, 0x14000
	v_add_u32_e32 v32, s26, v218
	ds_read_b128 v[210:213], v32
	ds_read_b128 v[214:217], v32 offset:1024
	ds_read_b128 v[236:239], v32 offset:2048
	ds_read_b128 v[240:243], v32 offset:3072
	s_add_i32 m0, s36, 0xc000
	s_nop 0
	global_load_lds_dwordx4 v206, s[2:3]
	ds_read_b128 v[90:93], v235
	ds_read_b128 v[94:97], v235 offset:1024
	ds_read_b128 v[106:109], v235 offset:2048
	ds_read_b128 v[110:113], v235 offset:3072
	ds_read_b128 v[162:165], v235 offset:4096
	ds_read_b128 v[166:169], v235 offset:5120
	ds_read_b128 v[170:173], v235 offset:6144
	ds_read_b128 v[174:177], v235 offset:7168
	s_add_i32 m0, s36, 0xe000
	s_nop 0
	global_load_lds_dwordx4 v208, s[2:3]
	s_waitcnt lgkmcnt(0)
	s_barrier
	s_setprio 1
	v_mfma_f32_16x16x32_bf16 v[158:161], v[66:69], v[90:93], v[158:161]
	v_mfma_f32_16x16x32_bf16 v[154:157], v[82:85], v[90:93], v[154:157]
	v_mfma_f32_16x16x32_bf16 v[142:145], v[66:69], v[106:109], v[142:145]
	v_mfma_f32_16x16x32_bf16 v[138:141], v[82:85], v[106:109], v[138:141]
	v_mfma_f32_16x16x32_bf16 v[126:129], v[66:69], v[162:165], v[126:129]
	v_mfma_f32_16x16x32_bf16 v[122:125], v[82:85], v[162:165], v[122:125]
	v_mfma_f32_16x16x32_bf16 v[102:105], v[66:69], v[170:173], v[102:105]
	v_mfma_f32_16x16x32_bf16 v[98:101], v[82:85], v[170:173], v[98:101]
	v_mfma_f32_16x16x32_bf16 v[158:161], v[70:73], v[94:97], v[158:161]
	v_mfma_f32_16x16x32_bf16 v[154:157], v[86:89], v[94:97], v[154:157]
	v_mfma_f32_16x16x32_bf16 v[142:145], v[70:73], v[110:113], v[142:145]
	v_mfma_f32_16x16x32_bf16 v[138:141], v[86:89], v[110:113], v[138:141]
	v_mfma_f32_16x16x32_bf16 v[126:129], v[70:73], v[166:169], v[126:129]
	v_mfma_f32_16x16x32_bf16 v[122:125], v[86:89], v[166:169], v[122:125]
	v_mfma_f32_16x16x32_bf16 v[102:105], v[70:73], v[174:177], v[102:105]
	v_mfma_f32_16x16x32_bf16 v[98:101], v[86:89], v[174:177], v[98:101]
	v_mfma_f32_16x16x32_bf16 v[150:153], v[210:213], v[90:93], v[150:153]
	v_mfma_f32_16x16x32_bf16 v[90:93], v[236:239], v[90:93], v[146:149]
	v_mfma_f32_16x16x32_bf16 v[150:153], v[214:217], v[94:97], v[150:153]
	v_mfma_f32_16x16x32_bf16 v[90:93], v[240:243], v[94:97], v[90:93]
	v_mfma_f32_16x16x32_bf16 v[94:97], v[210:213], v[106:109], v[134:137]
	v_mfma_f32_16x16x32_bf16 v[106:109], v[236:239], v[106:109], v[130:133]
	v_mfma_f32_16x16x32_bf16 v[114:117], v[236:239], v[162:165], v[114:117]
	v_mfma_f32_16x16x32_bf16 v[78:81], v[210:213], v[170:173], v[78:81]
	v_mfma_f32_16x16x32_bf16 v[74:77], v[236:239], v[170:173], v[74:77]
	v_mfma_f32_16x16x32_bf16 v[94:97], v[214:217], v[110:113], v[94:97]
	v_mfma_f32_16x16x32_bf16 v[106:109], v[240:243], v[110:113], v[106:109]
	v_mfma_f32_16x16x32_bf16 v[110:113], v[210:213], v[162:165], v[118:121]
	v_mfma_f32_16x16x32_bf16 v[114:117], v[240:243], v[166:169], v[114:117]
	v_mfma_f32_16x16x32_bf16 v[78:81], v[214:217], v[174:177], v[78:81]
	v_mfma_f32_16x16x32_bf16 v[74:77], v[240:243], v[174:177], v[74:77]
	v_mfma_f32_16x16x32_bf16 v[110:113], v[214:217], v[166:169], v[110:113]
	s_setprio 0
	s_barrier
	ds_read_b128 v[118:121], v235 offset:16384
	ds_read_b128 v[130:133], v235 offset:17408
	ds_read_b128 v[134:137], v235 offset:18432
	ds_read_b128 v[146:149], v235 offset:19456
	ds_read_b128 v[162:165], v235 offset:20480
	ds_read_b128 v[166:169], v235 offset:21504
	ds_read_b128 v[170:173], v235 offset:22528
	ds_read_b128 v[174:177], v235 offset:23552
	s_add_i32 m0, s35, 0x10000
	s_nop 0
	global_load_lds_dwordx4 v184, s[4:5]
	s_add_i32 m0, s35, 0x12000
	s_nop 0
	global_load_lds_dwordx4 v180, s[4:5]
	s_mov_b32 m0, s36
	s_nop 0
	global_load_lds_dwordx4 v186, s[6:7]
	s_mov_b32 m0, s37
	s_nop 0
	global_load_lds_dwordx4 v182, s[6:7]
	s_add_u32 s24, s4, 0x80000
	s_addc_u32 s25, s5, 0
	s_add_i32 m0, s35, 0x14000
	s_nop 0
	global_load_lds_dwordx4 v184, s[24:25]
	s_add_i32 m0, s35, 0x16000
	s_nop 0
	global_load_lds_dwordx4 v180, s[24:25]
	s_waitcnt vmcnt(6)
	s_waitcnt lgkmcnt(0)
	s_barrier
	s_setprio 1
	v_mfma_f32_16x16x32_bf16 v[62:65], v[66:69], v[118:121], v[62:65]
	v_mfma_f32_16x16x32_bf16 v[58:61], v[82:85], v[118:121], v[58:61]
	v_mfma_f32_16x16x32_bf16 v[46:49], v[66:69], v[134:137], v[46:49]
	v_mfma_f32_16x16x32_bf16 v[42:45], v[82:85], v[134:137], v[42:45]
	v_mfma_f32_16x16x32_bf16 v[28:31], v[66:69], v[162:165], v[28:31]
	v_mfma_f32_16x16x32_bf16 v[24:27], v[82:85], v[162:165], v[24:27]
	v_mfma_f32_16x16x32_bf16 v[12:15], v[66:69], v[170:173], v[12:15]
	v_mfma_f32_16x16x32_bf16 v[8:11], v[82:85], v[170:173], v[8:11]
	v_mfma_f32_16x16x32_bf16 v[62:65], v[70:73], v[130:133], v[62:65]
	v_mfma_f32_16x16x32_bf16 v[58:61], v[86:89], v[130:133], v[58:61]
	v_mfma_f32_16x16x32_bf16 v[46:49], v[70:73], v[146:149], v[46:49]
	v_mfma_f32_16x16x32_bf16 v[42:45], v[86:89], v[146:149], v[42:45]
	v_mfma_f32_16x16x32_bf16 v[28:31], v[70:73], v[166:169], v[28:31]
	v_mfma_f32_16x16x32_bf16 v[24:27], v[86:89], v[166:169], v[24:27]
	v_mfma_f32_16x16x32_bf16 v[12:15], v[70:73], v[174:177], v[12:15]
	v_mfma_f32_16x16x32_bf16 v[8:11], v[86:89], v[174:177], v[8:11]
	v_mfma_f32_16x16x32_bf16 v[54:57], v[210:213], v[118:121], v[54:57]
	v_mfma_f32_16x16x32_bf16 v[50:53], v[236:239], v[118:121], v[50:53]
	v_mfma_f32_16x16x32_bf16 v[38:41], v[210:213], v[134:137], v[38:41]
	v_mfma_f32_16x16x32_bf16 v[34:37], v[236:239], v[134:137], v[34:37]
	v_mfma_f32_16x16x32_bf16 v[20:23], v[210:213], v[162:165], v[20:23]
	v_mfma_f32_16x16x32_bf16 v[16:19], v[236:239], v[162:165], v[16:19]
	v_mfma_f32_16x16x32_bf16 v[4:7], v[210:213], v[170:173], v[4:7]
	v_mfma_f32_16x16x32_bf16 v[0:3], v[236:239], v[170:173], v[0:3]
	v_mfma_f32_16x16x32_bf16 v[54:57], v[214:217], v[130:133], v[54:57]
	v_mfma_f32_16x16x32_bf16 v[50:53], v[240:243], v[130:133], v[50:53]
	v_mfma_f32_16x16x32_bf16 v[38:41], v[214:217], v[146:149], v[38:41]
	v_mfma_f32_16x16x32_bf16 v[34:37], v[240:243], v[146:149], v[34:37]
	v_mfma_f32_16x16x32_bf16 v[20:23], v[214:217], v[166:169], v[20:23]
	v_mfma_f32_16x16x32_bf16 v[16:19], v[240:243], v[166:169], v[16:19]
	v_mfma_f32_16x16x32_bf16 v[4:7], v[214:217], v[174:177], v[4:7]
	v_mfma_f32_16x16x32_bf16 v[0:3], v[240:243], v[174:177], v[0:3]
	s_setprio 0
	s_add_i32 s23, 0, 0x18000
	v_add_u32_e32 v32, s23, v218
	s_barrier
	ds_read_b128 v[66:69], v32
	ds_read_b128 v[70:73], v32 offset:1024
	ds_read_b128 v[82:85], v32 offset:2048
	ds_read_b128 v[86:89], v32 offset:3072
	s_add_u32 s6, s6, 0x80000
	s_addc_u32 s7, s7, 0
	s_add_i32 s24, 0, 0x1c000
	v_add_u32_e32 v32, s24, v218
	ds_read_b128 v[236:239], v32
	ds_read_b128 v[240:243], v32 offset:1024
	ds_read_b128 v[244:247], v32 offset:2048
	ds_read_b128 v[248:251], v32 offset:3072
	s_mov_b32 m0, s38
	s_nop 0
	global_load_lds_dwordx4 v186, s[6:7]
	ds_read_b128 v[118:121], v235 offset:32768
	ds_read_b128 v[130:133], v235 offset:33792
	ds_read_b128 v[162:165], v235 offset:34816
	ds_read_b128 v[166:169], v235 offset:35840
	ds_read_b128 v[170:173], v235 offset:36864
	ds_read_b128 v[174:177], v235 offset:37888
	ds_read_b128 v[210:213], v235 offset:38912
	ds_read_b128 v[214:217], v235 offset:39936
	s_mov_b32 m0, s39
	s_nop 0
	global_load_lds_dwordx4 v182, s[6:7]
	s_waitcnt lgkmcnt(0)
	s_barrier
	s_setprio 1
	v_mfma_f32_16x16x32_bf16 v[134:137], v[66:69], v[118:121], v[158:161]
	v_mfma_f32_16x16x32_bf16 v[158:161], v[70:73], v[130:133], v[134:137]
	v_mfma_f32_16x16x32_bf16 v[134:137], v[82:85], v[118:121], v[154:157]
	v_mfma_f32_16x16x32_bf16 v[154:157], v[86:89], v[130:133], v[134:137]
	v_mfma_f32_16x16x32_bf16 v[134:137], v[66:69], v[162:165], v[142:145]
	v_mfma_f32_16x16x32_bf16 v[142:145], v[70:73], v[166:169], v[134:137]
	v_mfma_f32_16x16x32_bf16 v[134:137], v[82:85], v[162:165], v[138:141]
	v_mfma_f32_16x16x32_bf16 v[126:129], v[66:69], v[170:173], v[126:129]
	v_mfma_f32_16x16x32_bf16 v[122:125], v[82:85], v[170:173], v[122:125]
	v_mfma_f32_16x16x32_bf16 v[102:105], v[66:69], v[210:213], v[102:105]
	v_mfma_f32_16x16x32_bf16 v[98:101], v[82:85], v[210:213], v[98:101]
	v_mfma_f32_16x16x32_bf16 v[138:141], v[86:89], v[166:169], v[134:137]
	v_mfma_f32_16x16x32_bf16 v[126:129], v[70:73], v[174:177], v[126:129]
	v_mfma_f32_16x16x32_bf16 v[122:125], v[86:89], v[174:177], v[122:125]
	v_mfma_f32_16x16x32_bf16 v[102:105], v[70:73], v[214:217], v[102:105]
	v_mfma_f32_16x16x32_bf16 v[98:101], v[86:89], v[214:217], v[98:101]
	v_mfma_f32_16x16x32_bf16 v[90:93], v[244:247], v[118:121], v[90:93]
	v_mfma_f32_16x16x32_bf16 v[134:137], v[236:239], v[118:121], v[150:153]
	v_mfma_f32_16x16x32_bf16 v[146:149], v[248:251], v[130:133], v[90:93]
	v_mfma_f32_16x16x32_bf16 v[90:93], v[236:239], v[162:165], v[94:97]
	v_mfma_f32_16x16x32_bf16 v[150:153], v[240:243], v[130:133], v[134:137]
	v_mfma_f32_16x16x32_bf16 v[134:137], v[240:243], v[166:169], v[90:93]
	v_mfma_f32_16x16x32_bf16 v[90:93], v[244:247], v[162:165], v[106:109]
	v_mfma_f32_16x16x32_bf16 v[130:133], v[248:251], v[166:169], v[90:93]
	v_mfma_f32_16x16x32_bf16 v[90:93], v[236:239], v[170:173], v[110:113]
	v_mfma_f32_16x16x32_bf16 v[118:121], v[240:243], v[174:177], v[90:93]
	v_mfma_f32_16x16x32_bf16 v[90:93], v[244:247], v[170:173], v[114:117]
	v_mfma_f32_16x16x32_bf16 v[78:81], v[236:239], v[210:213], v[78:81]
	v_mfma_f32_16x16x32_bf16 v[74:77], v[244:247], v[210:213], v[74:77]
	v_mfma_f32_16x16x32_bf16 v[114:117], v[248:251], v[174:177], v[90:93]
	v_mfma_f32_16x16x32_bf16 v[78:81], v[240:243], v[214:217], v[78:81]
	v_mfma_f32_16x16x32_bf16 v[74:77], v[248:251], v[214:217], v[74:77]
	s_setprio 0
	s_barrier
	ds_read_b128 v[90:93], v235 offset:49152
	ds_read_b128 v[94:97], v235 offset:50176
	ds_read_b128 v[106:109], v235 offset:51200
	ds_read_b128 v[110:113], v235 offset:52224
	ds_read_b128 v[162:165], v235 offset:53248
	ds_read_b128 v[166:169], v235 offset:54272
	ds_read_b128 v[170:173], v235 offset:55296
	ds_read_b128 v[174:177], v235 offset:56320
	s_add_u32 s4, s4, 0x80
	s_addc_u32 s5, s5, 0
	s_add_i32 m0, s35, 0x18000
	s_nop 0
	global_load_lds_dwordx4 v184, s[4:5]
	s_add_i32 m0, s35, 0x1a000
	s_nop 0
	global_load_lds_dwordx4 v180, s[4:5]
	s_add_u32 s6, s6, 0xfff80080
	s_addc_u32 s7, s7, -1
	s_mov_b32 m0, s40
	s_nop 0
	global_load_lds_dwordx4 v186, s[6:7]
	s_mov_b32 m0, s41
	s_nop 0
	global_load_lds_dwordx4 v182, s[6:7]
	s_add_u32 s4, s4, 0x80000
	s_addc_u32 s5, s5, 0
	s_add_i32 m0, s35, 0x1c000
	s_nop 0
	global_load_lds_dwordx4 v184, s[4:5]
	s_add_i32 m0, s35, 0x1e000
	s_nop 0
	global_load_lds_dwordx4 v180, s[4:5]
	s_waitcnt vmcnt(6)
	s_waitcnt lgkmcnt(0)
	s_barrier
	s_setprio 1
	v_mfma_f32_16x16x32_bf16 v[62:65], v[66:69], v[90:93], v[62:65]
	v_mfma_f32_16x16x32_bf16 v[58:61], v[82:85], v[90:93], v[58:61]
	v_mfma_f32_16x16x32_bf16 v[46:49], v[66:69], v[106:109], v[46:49]
	v_mfma_f32_16x16x32_bf16 v[42:45], v[82:85], v[106:109], v[42:45]
	v_mfma_f32_16x16x32_bf16 v[28:31], v[66:69], v[162:165], v[28:31]
	v_mfma_f32_16x16x32_bf16 v[24:27], v[82:85], v[162:165], v[24:27]
	v_mfma_f32_16x16x32_bf16 v[12:15], v[66:69], v[170:173], v[12:15]
	v_mfma_f32_16x16x32_bf16 v[8:11], v[82:85], v[170:173], v[8:11]
	v_mfma_f32_16x16x32_bf16 v[62:65], v[70:73], v[94:97], v[62:65]
	v_mfma_f32_16x16x32_bf16 v[58:61], v[86:89], v[94:97], v[58:61]
	v_mfma_f32_16x16x32_bf16 v[46:49], v[70:73], v[110:113], v[46:49]
	v_mfma_f32_16x16x32_bf16 v[42:45], v[86:89], v[110:113], v[42:45]
	v_mfma_f32_16x16x32_bf16 v[28:31], v[70:73], v[166:169], v[28:31]
	v_mfma_f32_16x16x32_bf16 v[24:27], v[86:89], v[166:169], v[24:27]
	v_mfma_f32_16x16x32_bf16 v[12:15], v[70:73], v[174:177], v[12:15]
	v_mfma_f32_16x16x32_bf16 v[8:11], v[86:89], v[174:177], v[8:11]
	v_mfma_f32_16x16x32_bf16 v[54:57], v[236:239], v[90:93], v[54:57]
	v_mfma_f32_16x16x32_bf16 v[50:53], v[244:247], v[90:93], v[50:53]
	v_mfma_f32_16x16x32_bf16 v[38:41], v[236:239], v[106:109], v[38:41]
	v_mfma_f32_16x16x32_bf16 v[34:37], v[244:247], v[106:109], v[34:37]
	v_mfma_f32_16x16x32_bf16 v[20:23], v[236:239], v[162:165], v[20:23]
	v_mfma_f32_16x16x32_bf16 v[16:19], v[244:247], v[162:165], v[16:19]
	v_mfma_f32_16x16x32_bf16 v[4:7], v[236:239], v[170:173], v[4:7]
	v_mfma_f32_16x16x32_bf16 v[0:3], v[244:247], v[170:173], v[0:3]
	v_mfma_f32_16x16x32_bf16 v[54:57], v[240:243], v[94:97], v[54:57]
	v_mfma_f32_16x16x32_bf16 v[50:53], v[248:251], v[94:97], v[50:53]
	v_mfma_f32_16x16x32_bf16 v[38:41], v[240:243], v[110:113], v[38:41]
	v_mfma_f32_16x16x32_bf16 v[34:37], v[248:251], v[110:113], v[34:37]
	v_mfma_f32_16x16x32_bf16 v[20:23], v[240:243], v[166:169], v[20:23]
	v_mfma_f32_16x16x32_bf16 v[16:19], v[248:251], v[166:169], v[16:19]
	v_mfma_f32_16x16x32_bf16 v[4:7], v[240:243], v[174:177], v[4:7]
	v_mfma_f32_16x16x32_bf16 v[0:3], v[248:251], v[174:177], v[0:3]
	s_setprio 0
	s_add_i32 s15, s15, 2
	s_add_u32 s2, s2, 0x100
	s_addc_u32 s3, s3, 0
	s_add_u32 s9, s9, 0x100
	s_addc_u32 s13, s13, 0
	s_cmp_gt_u32 s15, 29
	s_barrier
	s_cbranch_scc0 .LBB0_1203
	v_mul_u32_u24_e32 v226, 0x3000, v189
	v_lshl_add_u32 v226, v188, 1, v226
	s_mul_i32 s26, s21, 0x300000
	s_lshl_b32 s2, s22, 12
	s_add_i32 s26, s26, s2
	s_lshl_b32 s2, s20, 9
	s_add_i32 s26, s26, s2
	s_add_i32 s26, s26, 0x37f51000
	s_add_u32 s26, s76, s26
	s_addc_u32 s27, s77, 0
	s_cmp_eq_u32 s22, 2
	s_cbranch_scc1 .Lbr_epi_final
	s_add_u32 s2, s26, 0
	s_addc_u32 s3, s27, 0
	s_add_u32 s4, s2, 0x30000
	s_addc_u32 s5, s3, 0
	s_add_u32 s6, s2, 0x1000
	s_addc_u32 s7, s3, 0
	s_add_u32 s24, s4, 0x1000
	s_addc_u32 s25, s5, 0
	global_load_dwordx4 v[66:69], v226, s[2:3]
	global_load_dwordx4 v[70:73], v226, s[6:7]
	global_load_dwordx4 v[82:85], v226, s[2:3] offset:256
	global_load_dwordx4 v[86:89], v226, s[6:7] offset:256
	global_load_dwordx4 v[90:93], v226, s[4:5]
	global_load_dwordx4 v[94:97], v226, s[24:25]
	global_load_dwordx4 v[106:109], v226, s[4:5] offset:256
	global_load_dwordx4 v[110:113], v226, s[24:25] offset:256
	s_add_u32 s2, s26, 0x60000
	s_addc_u32 s3, s27, 0
	s_add_u32 s4, s2, 0x30000
	s_addc_u32 s5, s3, 0
	s_add_u32 s6, s2, 0x1000
	s_addc_u32 s7, s3, 0
	s_add_u32 s24, s4, 0x1000
	s_addc_u32 s25, s5, 0
	global_load_dwordx4 v[162:165], v226, s[2:3]
	global_load_dwordx4 v[166:169], v226, s[6:7]
	global_load_dwordx4 v[170:173], v226, s[2:3] offset:256
	global_load_dwordx4 v[174:177], v226, s[6:7] offset:256
	global_load_dwordx4 v[210:213], v226, s[4:5]
	global_load_dwordx4 v[214:217], v226, s[24:25]
	global_load_dwordx4 v[236:239], v226, s[4:5] offset:256
	global_load_dwordx4 v[240:243], v226, s[24:25] offset:256
	s_waitcnt vmcnt(8)
	v_lshlrev_b32_e32 v246, 16, v70
	v_and_b32_e32 v247, 0xffff0000, v70
	v_lshlrev_b32_e32 v250, 16, v71
	v_and_b32_e32 v251, 0xffff0000, v71
	v_max_f32_e32 v246, 0x0da24260, v246
	v_max_f32_e32 v247, 0x0da24260, v247
	v_max_f32_e32 v250, 0x0da24260, v250
	v_max_f32_e32 v251, 0x0da24260, v251
	v_rcp_f32_e32 v246, v246
	v_rcp_f32_e32 v247, v247
	v_rcp_f32_e32 v250, v250
	v_rcp_f32_e32 v251, v251
	v_lshlrev_b32_e32 v244, 16, v66
	v_and_b32_e32 v245, 0xffff0000, v66
	v_lshlrev_b32_e32 v248, 16, v67
	v_and_b32_e32 v249, 0xffff0000, v67
	v_pk_mul_f32 v[158:159], v[158:159], v[244:245]
	v_pk_mul_f32 v[160:161], v[160:161], v[248:249]
	v_pk_mul_f32 v[158:159], v[158:159], v[246:247]
	v_pk_mul_f32 v[160:161], v[160:161], v[250:251]
	v_lshlrev_b32_e32 v246, 16, v72
	v_and_b32_e32 v247, 0xffff0000, v72
	v_lshlrev_b32_e32 v250, 16, v73
	v_and_b32_e32 v251, 0xffff0000, v73
	v_max_f32_e32 v246, 0x0da24260, v246
	v_max_f32_e32 v247, 0x0da24260, v247
	v_max_f32_e32 v250, 0x0da24260, v250
	v_max_f32_e32 v251, 0x0da24260, v251
	v_rcp_f32_e32 v246, v246
	v_rcp_f32_e32 v247, v247
	v_rcp_f32_e32 v250, v250
	v_rcp_f32_e32 v251, v251
	v_lshlrev_b32_e32 v244, 16, v68
	v_and_b32_e32 v245, 0xffff0000, v68
	v_lshlrev_b32_e32 v248, 16, v69
	v_and_b32_e32 v249, 0xffff0000, v69
	v_pk_mul_f32 v[154:155], v[154:155], v[244:245]
	v_pk_mul_f32 v[156:157], v[156:157], v[248:249]
	v_pk_mul_f32 v[154:155], v[154:155], v[246:247]
	v_pk_mul_f32 v[156:157], v[156:157], v[250:251]
	v_lshlrev_b32_e32 v246, 16, v86
	v_and_b32_e32 v247, 0xffff0000, v86
	v_lshlrev_b32_e32 v250, 16, v87
	v_and_b32_e32 v251, 0xffff0000, v87
	v_max_f32_e32 v246, 0x0da24260, v246
	v_max_f32_e32 v247, 0x0da24260, v247
	v_max_f32_e32 v250, 0x0da24260, v250
	v_max_f32_e32 v251, 0x0da24260, v251
	v_rcp_f32_e32 v246, v246
	v_rcp_f32_e32 v247, v247
	v_rcp_f32_e32 v250, v250
	v_rcp_f32_e32 v251, v251
	v_lshlrev_b32_e32 v244, 16, v82
	v_and_b32_e32 v245, 0xffff0000, v82
	v_lshlrev_b32_e32 v248, 16, v83
	v_and_b32_e32 v249, 0xffff0000, v83
	v_pk_mul_f32 v[150:151], v[150:151], v[244:245]
	v_pk_mul_f32 v[152:153], v[152:153], v[248:249]
	v_pk_mul_f32 v[150:151], v[150:151], v[246:247]
	v_pk_mul_f32 v[152:153], v[152:153], v[250:251]
	v_lshlrev_b32_e32 v246, 16, v88
	v_and_b32_e32 v247, 0xffff0000, v88
	v_lshlrev_b32_e32 v250, 16, v89
	v_and_b32_e32 v251, 0xffff0000, v89
	v_max_f32_e32 v246, 0x0da24260, v246
	v_max_f32_e32 v247, 0x0da24260, v247
	v_max_f32_e32 v250, 0x0da24260, v250
	v_max_f32_e32 v251, 0x0da24260, v251
	v_rcp_f32_e32 v246, v246
	v_rcp_f32_e32 v247, v247
	v_rcp_f32_e32 v250, v250
	v_rcp_f32_e32 v251, v251
	v_lshlrev_b32_e32 v244, 16, v84
	v_and_b32_e32 v245, 0xffff0000, v84
	v_lshlrev_b32_e32 v248, 16, v85
	v_and_b32_e32 v249, 0xffff0000, v85
	v_pk_mul_f32 v[146:147], v[146:147], v[244:245]
	v_pk_mul_f32 v[148:149], v[148:149], v[248:249]
	v_pk_mul_f32 v[146:147], v[146:147], v[246:247]
	v_pk_mul_f32 v[148:149], v[148:149], v[250:251]
	v_lshlrev_b32_e32 v246, 16, v94
	v_and_b32_e32 v247, 0xffff0000, v94
	v_lshlrev_b32_e32 v250, 16, v95
	v_and_b32_e32 v251, 0xffff0000, v95
	v_max_f32_e32 v246, 0x0da24260, v246
	v_max_f32_e32 v247, 0x0da24260, v247
	v_max_f32_e32 v250, 0x0da24260, v250
	v_max_f32_e32 v251, 0x0da24260, v251
	v_rcp_f32_e32 v246, v246
	v_rcp_f32_e32 v247, v247
	v_rcp_f32_e32 v250, v250
	v_rcp_f32_e32 v251, v251
	v_lshlrev_b32_e32 v244, 16, v90
	v_and_b32_e32 v245, 0xffff0000, v90
	v_lshlrev_b32_e32 v248, 16, v91
	v_and_b32_e32 v249, 0xffff0000, v91
	v_pk_mul_f32 v[142:143], v[142:143], v[244:245]
	v_pk_mul_f32 v[144:145], v[144:145], v[248:249]
	v_pk_mul_f32 v[142:143], v[142:143], v[246:247]
	v_pk_mul_f32 v[144:145], v[144:145], v[250:251]
	v_lshlrev_b32_e32 v246, 16, v96
	v_and_b32_e32 v247, 0xffff0000, v96
	v_lshlrev_b32_e32 v250, 16, v97
	v_and_b32_e32 v251, 0xffff0000, v97
	v_max_f32_e32 v246, 0x0da24260, v246
	v_max_f32_e32 v247, 0x0da24260, v247
	v_max_f32_e32 v250, 0x0da24260, v250
	v_max_f32_e32 v251, 0x0da24260, v251
	v_rcp_f32_e32 v246, v246
	v_rcp_f32_e32 v247, v247
	v_rcp_f32_e32 v250, v250
	v_rcp_f32_e32 v251, v251
	v_lshlrev_b32_e32 v244, 16, v92
	v_and_b32_e32 v245, 0xffff0000, v92
	v_lshlrev_b32_e32 v248, 16, v93
	v_and_b32_e32 v249, 0xffff0000, v93
	v_pk_mul_f32 v[138:139], v[138:139], v[244:245]
	v_pk_mul_f32 v[140:141], v[140:141], v[248:249]
	v_pk_mul_f32 v[138:139], v[138:139], v[246:247]
	v_pk_mul_f32 v[140:141], v[140:141], v[250:251]
	v_lshlrev_b32_e32 v246, 16, v110
	v_and_b32_e32 v247, 0xffff0000, v110
	v_lshlrev_b32_e32 v250, 16, v111
	v_and_b32_e32 v251, 0xffff0000, v111
	v_max_f32_e32 v246, 0x0da24260, v246
	v_max_f32_e32 v247, 0x0da24260, v247
	v_max_f32_e32 v250, 0x0da24260, v250
	v_max_f32_e32 v251, 0x0da24260, v251
	v_rcp_f32_e32 v246, v246
	v_rcp_f32_e32 v247, v247
	v_rcp_f32_e32 v250, v250
	v_rcp_f32_e32 v251, v251
	v_lshlrev_b32_e32 v244, 16, v106
	v_and_b32_e32 v245, 0xffff0000, v106
	v_lshlrev_b32_e32 v248, 16, v107
	v_and_b32_e32 v249, 0xffff0000, v107
	v_pk_mul_f32 v[134:135], v[134:135], v[244:245]
	v_pk_mul_f32 v[136:137], v[136:137], v[248:249]
	v_pk_mul_f32 v[134:135], v[134:135], v[246:247]
	v_pk_mul_f32 v[136:137], v[136:137], v[250:251]
	v_lshlrev_b32_e32 v246, 16, v112
	v_and_b32_e32 v247, 0xffff0000, v112
	v_lshlrev_b32_e32 v250, 16, v113
	v_and_b32_e32 v251, 0xffff0000, v113
	v_max_f32_e32 v246, 0x0da24260, v246
	v_max_f32_e32 v247, 0x0da24260, v247
	v_max_f32_e32 v250, 0x0da24260, v250
	v_max_f32_e32 v251, 0x0da24260, v251
	v_rcp_f32_e32 v246, v246
	v_rcp_f32_e32 v247, v247
	v_rcp_f32_e32 v250, v250
	v_rcp_f32_e32 v251, v251
	v_lshlrev_b32_e32 v244, 16, v108
	v_and_b32_e32 v245, 0xffff0000, v108
	v_lshlrev_b32_e32 v248, 16, v109
	v_and_b32_e32 v249, 0xffff0000, v109
	v_pk_mul_f32 v[130:131], v[130:131], v[244:245]
	v_pk_mul_f32 v[132:133], v[132:133], v[248:249]
	v_pk_mul_f32 v[130:131], v[130:131], v[246:247]
	v_pk_mul_f32 v[132:133], v[132:133], v[250:251]
	s_add_u32 s2, s26, 0x180000
	s_addc_u32 s3, s27, 0
	s_add_u32 s4, s2, 0x30000
	s_addc_u32 s5, s3, 0
	s_add_u32 s6, s2, 0x1000
	s_addc_u32 s7, s3, 0
	s_add_u32 s24, s4, 0x1000
	s_addc_u32 s25, s5, 0
	global_load_dwordx4 v[66:69], v226, s[2:3]
	global_load_dwordx4 v[70:73], v226, s[6:7]
	global_load_dwordx4 v[82:85], v226, s[2:3] offset:256
	global_load_dwordx4 v[86:89], v226, s[6:7] offset:256
	global_load_dwordx4 v[90:93], v226, s[4:5]
	global_load_dwordx4 v[94:97], v226, s[24:25]
	global_load_dwordx4 v[106:109], v226, s[4:5] offset:256
	global_load_dwordx4 v[110:113], v226, s[24:25] offset:256
	s_waitcnt vmcnt(8)
	v_lshlrev_b32_e32 v246, 16, v166
	v_and_b32_e32 v247, 0xffff0000, v166
	v_lshlrev_b32_e32 v250, 16, v167
	v_and_b32_e32 v251, 0xffff0000, v167
	v_max_f32_e32 v246, 0x0da24260, v246
	v_max_f32_e32 v247, 0x0da24260, v247
	v_max_f32_e32 v250, 0x0da24260, v250
	v_max_f32_e32 v251, 0x0da24260, v251
	v_rcp_f32_e32 v246, v246
	v_rcp_f32_e32 v247, v247
	v_rcp_f32_e32 v250, v250
	v_rcp_f32_e32 v251, v251
	v_lshlrev_b32_e32 v244, 16, v162
	v_and_b32_e32 v245, 0xffff0000, v162
	v_lshlrev_b32_e32 v248, 16, v163
	v_and_b32_e32 v249, 0xffff0000, v163
	v_pk_mul_f32 v[126:127], v[126:127], v[244:245]
	v_pk_mul_f32 v[128:129], v[128:129], v[248:249]
	v_pk_mul_f32 v[126:127], v[126:127], v[246:247]
	v_pk_mul_f32 v[128:129], v[128:129], v[250:251]
	v_lshlrev_b32_e32 v246, 16, v168
	v_and_b32_e32 v247, 0xffff0000, v168
	v_lshlrev_b32_e32 v250, 16, v169
	v_and_b32_e32 v251, 0xffff0000, v169
	v_max_f32_e32 v246, 0x0da24260, v246
	v_max_f32_e32 v247, 0x0da24260, v247
	v_max_f32_e32 v250, 0x0da24260, v250
	v_max_f32_e32 v251, 0x0da24260, v251
	v_rcp_f32_e32 v246, v246
	v_rcp_f32_e32 v247, v247
	v_rcp_f32_e32 v250, v250
	v_rcp_f32_e32 v251, v251
	v_lshlrev_b32_e32 v244, 16, v164
	v_and_b32_e32 v245, 0xffff0000, v164
	v_lshlrev_b32_e32 v248, 16, v165
	v_and_b32_e32 v249, 0xffff0000, v165
	v_pk_mul_f32 v[122:123], v[122:123], v[244:245]
	v_pk_mul_f32 v[124:125], v[124:125], v[248:249]
	v_pk_mul_f32 v[122:123], v[122:123], v[246:247]
	v_pk_mul_f32 v[124:125], v[124:125], v[250:251]
	v_lshlrev_b32_e32 v246, 16, v174
	v_and_b32_e32 v247, 0xffff0000, v174
	v_lshlrev_b32_e32 v250, 16, v175
	v_and_b32_e32 v251, 0xffff0000, v175
	v_max_f32_e32 v246, 0x0da24260, v246
	v_max_f32_e32 v247, 0x0da24260, v247
	v_max_f32_e32 v250, 0x0da24260, v250
	v_max_f32_e32 v251, 0x0da24260, v251
	v_rcp_f32_e32 v246, v246
	v_rcp_f32_e32 v247, v247
	v_rcp_f32_e32 v250, v250
	v_rcp_f32_e32 v251, v251
	v_lshlrev_b32_e32 v244, 16, v170
	v_and_b32_e32 v245, 0xffff0000, v170
	v_lshlrev_b32_e32 v248, 16, v171
	v_and_b32_e32 v249, 0xffff0000, v171
	v_pk_mul_f32 v[118:119], v[118:119], v[244:245]
	v_pk_mul_f32 v[120:121], v[120:121], v[248:249]
	v_pk_mul_f32 v[118:119], v[118:119], v[246:247]
	v_pk_mul_f32 v[120:121], v[120:121], v[250:251]
	v_lshlrev_b32_e32 v246, 16, v176
	v_and_b32_e32 v247, 0xffff0000, v176
	v_lshlrev_b32_e32 v250, 16, v177
	v_and_b32_e32 v251, 0xffff0000, v177
	v_max_f32_e32 v246, 0x0da24260, v246
	v_max_f32_e32 v247, 0x0da24260, v247
	v_max_f32_e32 v250, 0x0da24260, v250
	v_max_f32_e32 v251, 0x0da24260, v251
	v_rcp_f32_e32 v246, v246
	v_rcp_f32_e32 v247, v247
	v_rcp_f32_e32 v250, v250
	v_rcp_f32_e32 v251, v251
	v_lshlrev_b32_e32 v244, 16, v172
	v_and_b32_e32 v245, 0xffff0000, v172
	v_lshlrev_b32_e32 v248, 16, v173
	v_and_b32_e32 v249, 0xffff0000, v173
	v_pk_mul_f32 v[114:115], v[114:115], v[244:245]
	v_pk_mul_f32 v[116:117], v[116:117], v[248:249]
	v_pk_mul_f32 v[114:115], v[114:115], v[246:247]
	v_pk_mul_f32 v[116:117], v[116:117], v[250:251]
	v_lshlrev_b32_e32 v246, 16, v214
	v_and_b32_e32 v247, 0xffff0000, v214
	v_lshlrev_b32_e32 v250, 16, v215
	v_and_b32_e32 v251, 0xffff0000, v215
	v_max_f32_e32 v246, 0x0da24260, v246
	v_max_f32_e32 v247, 0x0da24260, v247
	v_max_f32_e32 v250, 0x0da24260, v250
	v_max_f32_e32 v251, 0x0da24260, v251
	v_rcp_f32_e32 v246, v246
	v_rcp_f32_e32 v247, v247
	v_rcp_f32_e32 v250, v250
	v_rcp_f32_e32 v251, v251
	v_lshlrev_b32_e32 v244, 16, v210
	v_and_b32_e32 v245, 0xffff0000, v210
	v_lshlrev_b32_e32 v248, 16, v211
	v_and_b32_e32 v249, 0xffff0000, v211
	v_pk_mul_f32 v[102:103], v[102:103], v[244:245]
	v_pk_mul_f32 v[104:105], v[104:105], v[248:249]
	v_pk_mul_f32 v[102:103], v[102:103], v[246:247]
	v_pk_mul_f32 v[104:105], v[104:105], v[250:251]
	v_lshlrev_b32_e32 v246, 16, v216
	v_and_b32_e32 v247, 0xffff0000, v216
	v_lshlrev_b32_e32 v250, 16, v217
	v_and_b32_e32 v251, 0xffff0000, v217
	v_max_f32_e32 v246, 0x0da24260, v246
	v_max_f32_e32 v247, 0x0da24260, v247
	v_max_f32_e32 v250, 0x0da24260, v250
	v_max_f32_e32 v251, 0x0da24260, v251
	v_rcp_f32_e32 v246, v246
	v_rcp_f32_e32 v247, v247
	v_rcp_f32_e32 v250, v250
	v_rcp_f32_e32 v251, v251
	v_lshlrev_b32_e32 v244, 16, v212
	v_and_b32_e32 v245, 0xffff0000, v212
	v_lshlrev_b32_e32 v248, 16, v213
	v_and_b32_e32 v249, 0xffff0000, v213
	v_pk_mul_f32 v[98:99], v[98:99], v[244:245]
	v_pk_mul_f32 v[100:101], v[100:101], v[248:249]
	v_pk_mul_f32 v[98:99], v[98:99], v[246:247]
	v_pk_mul_f32 v[100:101], v[100:101], v[250:251]
	v_lshlrev_b32_e32 v246, 16, v240
	v_and_b32_e32 v247, 0xffff0000, v240
	v_lshlrev_b32_e32 v250, 16, v241
	v_and_b32_e32 v251, 0xffff0000, v241
	v_max_f32_e32 v246, 0x0da24260, v246
	v_max_f32_e32 v247, 0x0da24260, v247
	v_max_f32_e32 v250, 0x0da24260, v250
	v_max_f32_e32 v251, 0x0da24260, v251
	v_rcp_f32_e32 v246, v246
	v_rcp_f32_e32 v247, v247
	v_rcp_f32_e32 v250, v250
	v_rcp_f32_e32 v251, v251
	v_lshlrev_b32_e32 v244, 16, v236
	v_and_b32_e32 v245, 0xffff0000, v236
	v_lshlrev_b32_e32 v248, 16, v237
	v_and_b32_e32 v249, 0xffff0000, v237
	v_pk_mul_f32 v[78:79], v[78:79], v[244:245]
	v_pk_mul_f32 v[80:81], v[80:81], v[248:249]
	v_pk_mul_f32 v[78:79], v[78:79], v[246:247]
	v_pk_mul_f32 v[80:81], v[80:81], v[250:251]
	v_lshlrev_b32_e32 v246, 16, v242
	v_and_b32_e32 v247, 0xffff0000, v242
	v_lshlrev_b32_e32 v250, 16, v243
	v_and_b32_e32 v251, 0xffff0000, v243
	v_max_f32_e32 v246, 0x0da24260, v246
	v_max_f32_e32 v247, 0x0da24260, v247
	v_max_f32_e32 v250, 0x0da24260, v250
	v_max_f32_e32 v251, 0x0da24260, v251
	v_rcp_f32_e32 v246, v246
	v_rcp_f32_e32 v247, v247
	v_rcp_f32_e32 v250, v250
	v_rcp_f32_e32 v251, v251
	v_lshlrev_b32_e32 v244, 16, v238
	v_and_b32_e32 v245, 0xffff0000, v238
	v_lshlrev_b32_e32 v248, 16, v239
	v_and_b32_e32 v249, 0xffff0000, v239
	v_pk_mul_f32 v[74:75], v[74:75], v[244:245]
	v_pk_mul_f32 v[76:77], v[76:77], v[248:249]
	v_pk_mul_f32 v[74:75], v[74:75], v[246:247]
	v_pk_mul_f32 v[76:77], v[76:77], v[250:251]
	s_add_u32 s2, s26, 0x1e0000
	s_addc_u32 s3, s27, 0
	s_add_u32 s4, s2, 0x30000
	s_addc_u32 s5, s3, 0
	s_add_u32 s6, s2, 0x1000
	s_addc_u32 s7, s3, 0
	s_add_u32 s24, s4, 0x1000
	s_addc_u32 s25, s5, 0
	global_load_dwordx4 v[162:165], v226, s[2:3]
	global_load_dwordx4 v[166:169], v226, s[6:7]
	global_load_dwordx4 v[170:173], v226, s[2:3] offset:256
	global_load_dwordx4 v[174:177], v226, s[6:7] offset:256
	global_load_dwordx4 v[210:213], v226, s[4:5]
	global_load_dwordx4 v[214:217], v226, s[24:25]
	global_load_dwordx4 v[236:239], v226, s[4:5] offset:256
	global_load_dwordx4 v[240:243], v226, s[24:25] offset:256
	s_waitcnt vmcnt(8)
	v_lshlrev_b32_e32 v246, 16, v70
	v_and_b32_e32 v247, 0xffff0000, v70
	v_lshlrev_b32_e32 v250, 16, v71
	v_and_b32_e32 v251, 0xffff0000, v71
	v_max_f32_e32 v246, 0x0da24260, v246
	v_max_f32_e32 v247, 0x0da24260, v247
	v_max_f32_e32 v250, 0x0da24260, v250
	v_max_f32_e32 v251, 0x0da24260, v251
	v_rcp_f32_e32 v246, v246
	v_rcp_f32_e32 v247, v247
	v_rcp_f32_e32 v250, v250
	v_rcp_f32_e32 v251, v251
	v_lshlrev_b32_e32 v244, 16, v66
	v_and_b32_e32 v245, 0xffff0000, v66
	v_lshlrev_b32_e32 v248, 16, v67
	v_and_b32_e32 v249, 0xffff0000, v67
	v_pk_mul_f32 v[62:63], v[62:63], v[244:245]
	v_pk_mul_f32 v[64:65], v[64:65], v[248:249]
	v_pk_mul_f32 v[62:63], v[62:63], v[246:247]
	v_pk_mul_f32 v[64:65], v[64:65], v[250:251]
	v_lshlrev_b32_e32 v246, 16, v72
	v_and_b32_e32 v247, 0xffff0000, v72
	v_lshlrev_b32_e32 v250, 16, v73
	v_and_b32_e32 v251, 0xffff0000, v73
	v_max_f32_e32 v246, 0x0da24260, v246
	v_max_f32_e32 v247, 0x0da24260, v247
	v_max_f32_e32 v250, 0x0da24260, v250
	v_max_f32_e32 v251, 0x0da24260, v251
	v_rcp_f32_e32 v246, v246
	v_rcp_f32_e32 v247, v247
	v_rcp_f32_e32 v250, v250
	v_rcp_f32_e32 v251, v251
	v_lshlrev_b32_e32 v244, 16, v68
	v_and_b32_e32 v245, 0xffff0000, v68
	v_lshlrev_b32_e32 v248, 16, v69
	v_and_b32_e32 v249, 0xffff0000, v69
	v_pk_mul_f32 v[58:59], v[58:59], v[244:245]
	v_pk_mul_f32 v[60:61], v[60:61], v[248:249]
	v_pk_mul_f32 v[58:59], v[58:59], v[246:247]
	v_pk_mul_f32 v[60:61], v[60:61], v[250:251]
	v_lshlrev_b32_e32 v246, 16, v86
	v_and_b32_e32 v247, 0xffff0000, v86
	v_lshlrev_b32_e32 v250, 16, v87
	v_and_b32_e32 v251, 0xffff0000, v87
	v_max_f32_e32 v246, 0x0da24260, v246
	v_max_f32_e32 v247, 0x0da24260, v247
	v_max_f32_e32 v250, 0x0da24260, v250
	v_max_f32_e32 v251, 0x0da24260, v251
	v_rcp_f32_e32 v246, v246
	v_rcp_f32_e32 v247, v247
	v_rcp_f32_e32 v250, v250
	v_rcp_f32_e32 v251, v251
	v_lshlrev_b32_e32 v244, 16, v82
	v_and_b32_e32 v245, 0xffff0000, v82
	v_lshlrev_b32_e32 v248, 16, v83
	v_and_b32_e32 v249, 0xffff0000, v83
	v_pk_mul_f32 v[54:55], v[54:55], v[244:245]
	v_pk_mul_f32 v[56:57], v[56:57], v[248:249]
	v_pk_mul_f32 v[54:55], v[54:55], v[246:247]
	v_pk_mul_f32 v[56:57], v[56:57], v[250:251]
	v_lshlrev_b32_e32 v246, 16, v88
	v_and_b32_e32 v247, 0xffff0000, v88
	v_lshlrev_b32_e32 v250, 16, v89
	v_and_b32_e32 v251, 0xffff0000, v89
	v_max_f32_e32 v246, 0x0da24260, v246
	v_max_f32_e32 v247, 0x0da24260, v247
	v_max_f32_e32 v250, 0x0da24260, v250
	v_max_f32_e32 v251, 0x0da24260, v251
	v_rcp_f32_e32 v246, v246
	v_rcp_f32_e32 v247, v247
	v_rcp_f32_e32 v250, v250
	v_rcp_f32_e32 v251, v251
	v_lshlrev_b32_e32 v244, 16, v84
	v_and_b32_e32 v245, 0xffff0000, v84
	v_lshlrev_b32_e32 v248, 16, v85
	v_and_b32_e32 v249, 0xffff0000, v85
	v_pk_mul_f32 v[50:51], v[50:51], v[244:245]
	v_pk_mul_f32 v[52:53], v[52:53], v[248:249]
	v_pk_mul_f32 v[50:51], v[50:51], v[246:247]
	v_pk_mul_f32 v[52:53], v[52:53], v[250:251]
	v_lshlrev_b32_e32 v246, 16, v94
	v_and_b32_e32 v247, 0xffff0000, v94
	v_lshlrev_b32_e32 v250, 16, v95
	v_and_b32_e32 v251, 0xffff0000, v95
	v_max_f32_e32 v246, 0x0da24260, v246
	v_max_f32_e32 v247, 0x0da24260, v247
	v_max_f32_e32 v250, 0x0da24260, v250
	v_max_f32_e32 v251, 0x0da24260, v251
	v_rcp_f32_e32 v246, v246
	v_rcp_f32_e32 v247, v247
	v_rcp_f32_e32 v250, v250
	v_rcp_f32_e32 v251, v251
	v_lshlrev_b32_e32 v244, 16, v90
	v_and_b32_e32 v245, 0xffff0000, v90
	v_lshlrev_b32_e32 v248, 16, v91
	v_and_b32_e32 v249, 0xffff0000, v91
	v_pk_mul_f32 v[46:47], v[46:47], v[244:245]
	v_pk_mul_f32 v[48:49], v[48:49], v[248:249]
	v_pk_mul_f32 v[46:47], v[46:47], v[246:247]
	v_pk_mul_f32 v[48:49], v[48:49], v[250:251]
	v_lshlrev_b32_e32 v246, 16, v96
	v_and_b32_e32 v247, 0xffff0000, v96
	v_lshlrev_b32_e32 v250, 16, v97
	v_and_b32_e32 v251, 0xffff0000, v97
	v_max_f32_e32 v246, 0x0da24260, v246
	v_max_f32_e32 v247, 0x0da24260, v247
	v_max_f32_e32 v250, 0x0da24260, v250
	v_max_f32_e32 v251, 0x0da24260, v251
	v_rcp_f32_e32 v246, v246
	v_rcp_f32_e32 v247, v247
	v_rcp_f32_e32 v250, v250
	v_rcp_f32_e32 v251, v251
	v_lshlrev_b32_e32 v244, 16, v92
	v_and_b32_e32 v245, 0xffff0000, v92
	v_lshlrev_b32_e32 v248, 16, v93
	v_and_b32_e32 v249, 0xffff0000, v93
	v_pk_mul_f32 v[42:43], v[42:43], v[244:245]
	v_pk_mul_f32 v[44:45], v[44:45], v[248:249]
	v_pk_mul_f32 v[42:43], v[42:43], v[246:247]
	v_pk_mul_f32 v[44:45], v[44:45], v[250:251]
	v_lshlrev_b32_e32 v246, 16, v110
	v_and_b32_e32 v247, 0xffff0000, v110
	v_lshlrev_b32_e32 v250, 16, v111
	v_and_b32_e32 v251, 0xffff0000, v111
	v_max_f32_e32 v246, 0x0da24260, v246
	v_max_f32_e32 v247, 0x0da24260, v247
	v_max_f32_e32 v250, 0x0da24260, v250
	v_max_f32_e32 v251, 0x0da24260, v251
	v_rcp_f32_e32 v246, v246
	v_rcp_f32_e32 v247, v247
	v_rcp_f32_e32 v250, v250
	v_rcp_f32_e32 v251, v251
	v_lshlrev_b32_e32 v244, 16, v106
	v_and_b32_e32 v245, 0xffff0000, v106
	v_lshlrev_b32_e32 v248, 16, v107
	v_and_b32_e32 v249, 0xffff0000, v107
	v_pk_mul_f32 v[38:39], v[38:39], v[244:245]
	v_pk_mul_f32 v[40:41], v[40:41], v[248:249]
	v_pk_mul_f32 v[38:39], v[38:39], v[246:247]
	v_pk_mul_f32 v[40:41], v[40:41], v[250:251]
	v_lshlrev_b32_e32 v246, 16, v112
	v_and_b32_e32 v247, 0xffff0000, v112
	v_lshlrev_b32_e32 v250, 16, v113
	v_and_b32_e32 v251, 0xffff0000, v113
	v_max_f32_e32 v246, 0x0da24260, v246
	v_max_f32_e32 v247, 0x0da24260, v247
	v_max_f32_e32 v250, 0x0da24260, v250
	v_max_f32_e32 v251, 0x0da24260, v251
	v_rcp_f32_e32 v246, v246
	v_rcp_f32_e32 v247, v247
	v_rcp_f32_e32 v250, v250
	v_rcp_f32_e32 v251, v251
	v_lshlrev_b32_e32 v244, 16, v108
	v_and_b32_e32 v245, 0xffff0000, v108
	v_lshlrev_b32_e32 v248, 16, v109
	v_and_b32_e32 v249, 0xffff0000, v109
	v_pk_mul_f32 v[34:35], v[34:35], v[244:245]
	v_pk_mul_f32 v[36:37], v[36:37], v[248:249]
	v_pk_mul_f32 v[34:35], v[34:35], v[246:247]
	v_pk_mul_f32 v[36:37], v[36:37], v[250:251]
	s_waitcnt vmcnt(0)
	v_lshlrev_b32_e32 v246, 16, v166
	v_and_b32_e32 v247, 0xffff0000, v166
	v_lshlrev_b32_e32 v250, 16, v167
	v_and_b32_e32 v251, 0xffff0000, v167
	v_max_f32_e32 v246, 0x0da24260, v246
	v_max_f32_e32 v247, 0x0da24260, v247
	v_max_f32_e32 v250, 0x0da24260, v250
	v_max_f32_e32 v251, 0x0da24260, v251
	v_rcp_f32_e32 v246, v246
	v_rcp_f32_e32 v247, v247
	v_rcp_f32_e32 v250, v250
	v_rcp_f32_e32 v251, v251
	v_lshlrev_b32_e32 v244, 16, v162
	v_and_b32_e32 v245, 0xffff0000, v162
	v_lshlrev_b32_e32 v248, 16, v163
	v_and_b32_e32 v249, 0xffff0000, v163
	v_pk_mul_f32 v[28:29], v[28:29], v[244:245]
	v_pk_mul_f32 v[30:31], v[30:31], v[248:249]
	v_pk_mul_f32 v[28:29], v[28:29], v[246:247]
	v_pk_mul_f32 v[30:31], v[30:31], v[250:251]
	v_lshlrev_b32_e32 v246, 16, v168
	v_and_b32_e32 v247, 0xffff0000, v168
	v_lshlrev_b32_e32 v250, 16, v169
	v_and_b32_e32 v251, 0xffff0000, v169
	v_max_f32_e32 v246, 0x0da24260, v246
	v_max_f32_e32 v247, 0x0da24260, v247
	v_max_f32_e32 v250, 0x0da24260, v250
	v_max_f32_e32 v251, 0x0da24260, v251
	v_rcp_f32_e32 v246, v246
	v_rcp_f32_e32 v247, v247
	v_rcp_f32_e32 v250, v250
	v_rcp_f32_e32 v251, v251
	v_lshlrev_b32_e32 v244, 16, v164
	v_and_b32_e32 v245, 0xffff0000, v164
	v_lshlrev_b32_e32 v248, 16, v165
	v_and_b32_e32 v249, 0xffff0000, v165
	v_pk_mul_f32 v[24:25], v[24:25], v[244:245]
	v_pk_mul_f32 v[26:27], v[26:27], v[248:249]
	v_pk_mul_f32 v[24:25], v[24:25], v[246:247]
	v_pk_mul_f32 v[26:27], v[26:27], v[250:251]
	v_lshlrev_b32_e32 v246, 16, v174
	v_and_b32_e32 v247, 0xffff0000, v174
	v_lshlrev_b32_e32 v250, 16, v175
	v_and_b32_e32 v251, 0xffff0000, v175
	v_max_f32_e32 v246, 0x0da24260, v246
	v_max_f32_e32 v247, 0x0da24260, v247
	v_max_f32_e32 v250, 0x0da24260, v250
	v_max_f32_e32 v251, 0x0da24260, v251
	v_rcp_f32_e32 v246, v246
	v_rcp_f32_e32 v247, v247
	v_rcp_f32_e32 v250, v250
	v_rcp_f32_e32 v251, v251
	v_lshlrev_b32_e32 v244, 16, v170
	v_and_b32_e32 v245, 0xffff0000, v170
	v_lshlrev_b32_e32 v248, 16, v171
	v_and_b32_e32 v249, 0xffff0000, v171
	v_pk_mul_f32 v[20:21], v[20:21], v[244:245]
	v_pk_mul_f32 v[22:23], v[22:23], v[248:249]
	v_pk_mul_f32 v[20:21], v[20:21], v[246:247]
	v_pk_mul_f32 v[22:23], v[22:23], v[250:251]
	v_lshlrev_b32_e32 v246, 16, v176
	v_and_b32_e32 v247, 0xffff0000, v176
	v_lshlrev_b32_e32 v250, 16, v177
	v_and_b32_e32 v251, 0xffff0000, v177
	v_max_f32_e32 v246, 0x0da24260, v246
	v_max_f32_e32 v247, 0x0da24260, v247
	v_max_f32_e32 v250, 0x0da24260, v250
	v_max_f32_e32 v251, 0x0da24260, v251
	v_rcp_f32_e32 v246, v246
	v_rcp_f32_e32 v247, v247
	v_rcp_f32_e32 v250, v250
	v_rcp_f32_e32 v251, v251
	v_lshlrev_b32_e32 v244, 16, v172
	v_and_b32_e32 v245, 0xffff0000, v172
	v_lshlrev_b32_e32 v248, 16, v173
	v_and_b32_e32 v249, 0xffff0000, v173
	v_pk_mul_f32 v[16:17], v[16:17], v[244:245]
	v_pk_mul_f32 v[18:19], v[18:19], v[248:249]
	v_pk_mul_f32 v[16:17], v[16:17], v[246:247]
	v_pk_mul_f32 v[18:19], v[18:19], v[250:251]
	v_lshlrev_b32_e32 v246, 16, v214
	v_and_b32_e32 v247, 0xffff0000, v214
	v_lshlrev_b32_e32 v250, 16, v215
	v_and_b32_e32 v251, 0xffff0000, v215
	v_max_f32_e32 v246, 0x0da24260, v246
	v_max_f32_e32 v247, 0x0da24260, v247
	v_max_f32_e32 v250, 0x0da24260, v250
	v_max_f32_e32 v251, 0x0da24260, v251
	v_rcp_f32_e32 v246, v246
	v_rcp_f32_e32 v247, v247
	v_rcp_f32_e32 v250, v250
	v_rcp_f32_e32 v251, v251
	v_lshlrev_b32_e32 v244, 16, v210
	v_and_b32_e32 v245, 0xffff0000, v210
	v_lshlrev_b32_e32 v248, 16, v211
	v_and_b32_e32 v249, 0xffff0000, v211
	v_pk_mul_f32 v[12:13], v[12:13], v[244:245]
	v_pk_mul_f32 v[14:15], v[14:15], v[248:249]
	v_pk_mul_f32 v[12:13], v[12:13], v[246:247]
	v_pk_mul_f32 v[14:15], v[14:15], v[250:251]
	v_lshlrev_b32_e32 v246, 16, v216
	v_and_b32_e32 v247, 0xffff0000, v216
	v_lshlrev_b32_e32 v250, 16, v217
	v_and_b32_e32 v251, 0xffff0000, v217
	v_max_f32_e32 v246, 0x0da24260, v246
	v_max_f32_e32 v247, 0x0da24260, v247
	v_max_f32_e32 v250, 0x0da24260, v250
	v_max_f32_e32 v251, 0x0da24260, v251
	v_rcp_f32_e32 v246, v246
	v_rcp_f32_e32 v247, v247
	v_rcp_f32_e32 v250, v250
	v_rcp_f32_e32 v251, v251
	v_lshlrev_b32_e32 v244, 16, v212
	v_and_b32_e32 v245, 0xffff0000, v212
	v_lshlrev_b32_e32 v248, 16, v213
	v_and_b32_e32 v249, 0xffff0000, v213
	v_pk_mul_f32 v[8:9], v[8:9], v[244:245]
	v_pk_mul_f32 v[10:11], v[10:11], v[248:249]
	v_pk_mul_f32 v[8:9], v[8:9], v[246:247]
	v_pk_mul_f32 v[10:11], v[10:11], v[250:251]
	v_lshlrev_b32_e32 v246, 16, v240
	v_and_b32_e32 v247, 0xffff0000, v240
	v_lshlrev_b32_e32 v250, 16, v241
	v_and_b32_e32 v251, 0xffff0000, v241
	v_max_f32_e32 v246, 0x0da24260, v246
	v_max_f32_e32 v247, 0x0da24260, v247
	v_max_f32_e32 v250, 0x0da24260, v250
	v_max_f32_e32 v251, 0x0da24260, v251
	v_rcp_f32_e32 v246, v246
	v_rcp_f32_e32 v247, v247
	v_rcp_f32_e32 v250, v250
	v_rcp_f32_e32 v251, v251
	v_lshlrev_b32_e32 v244, 16, v236
	v_and_b32_e32 v245, 0xffff0000, v236
	v_lshlrev_b32_e32 v248, 16, v237
	v_and_b32_e32 v249, 0xffff0000, v237
	v_pk_mul_f32 v[4:5], v[4:5], v[244:245]
	v_pk_mul_f32 v[6:7], v[6:7], v[248:249]
	v_pk_mul_f32 v[4:5], v[4:5], v[246:247]
	v_pk_mul_f32 v[6:7], v[6:7], v[250:251]
	v_lshlrev_b32_e32 v246, 16, v242
	v_and_b32_e32 v247, 0xffff0000, v242
	v_lshlrev_b32_e32 v250, 16, v243
	v_and_b32_e32 v251, 0xffff0000, v243
	v_max_f32_e32 v246, 0x0da24260, v246
	v_max_f32_e32 v247, 0x0da24260, v247
	v_max_f32_e32 v250, 0x0da24260, v250
	v_max_f32_e32 v251, 0x0da24260, v251
	v_rcp_f32_e32 v246, v246
	v_rcp_f32_e32 v247, v247
	v_rcp_f32_e32 v250, v250
	v_rcp_f32_e32 v251, v251
	v_lshlrev_b32_e32 v244, 16, v238
	v_and_b32_e32 v245, 0xffff0000, v238
	v_lshlrev_b32_e32 v248, 16, v239
	v_and_b32_e32 v249, 0xffff0000, v239
	v_pk_mul_f32 v[0:1], v[0:1], v[244:245]
	v_pk_mul_f32 v[2:3], v[2:3], v[248:249]
	v_pk_mul_f32 v[0:1], v[0:1], v[246:247]
	v_pk_mul_f32 v[2:3], v[2:3], v[250:251]
	s_branch .LBB0_1183

.LBB0_1375:
	s_add_u32 s16, s14, 0xfff80080
	s_addc_u32 s17, s15, -1
	s_add_i32 s40, 0, 0x10000
	v_add_u32_e32 v142, s40, v161
	ds_read_b128 v[130:133], v142
	ds_read_b128 v[134:137], v142 offset:1024
	ds_read_b128 v[138:141], v142 offset:2048
	ds_read_b128 v[142:145], v142 offset:3072
	s_cmp_eq_u32 s39, 28
	s_cselect_b32 s19, s5, s17
	s_cselect_b32 s18, s4, s16
	s_cselect_b32 s17, s7, s13
	s_cselect_b32 s16, s6, s11
	s_add_i32 s42, 0, 0x14000
	v_add_u32_e32 v176, s42, v161
	ds_read_b128 v[196:199], v176
	ds_read_b128 v[200:203], v176 offset:1024
	ds_read_b128 v[204:207], v176 offset:2048
	ds_read_b128 v[208:211], v176 offset:3072
	s_add_i32 m0, s24, 0xc000
	s_nop 0
	global_load_lds_dwordx4 v152, s[14:15]
	ds_read_b128 v[156:159], v163
	ds_read_b128 v[164:167], v163 offset:1024
	ds_read_b128 v[168:171], v163 offset:2048
	ds_read_b128 v[172:175], v163 offset:3072
	ds_read_b128 v[180:183], v163 offset:4096
	ds_read_b128 v[184:187], v163 offset:5120
	ds_read_b128 v[188:191], v163 offset:6144
	ds_read_b128 v[192:195], v163 offset:7168
	s_add_i32 m0, s24, 0xe000
	s_nop 0
	global_load_lds_dwordx4 v154, s[14:15]
	s_waitcnt lgkmcnt(0)
	s_barrier
	s_setprio 1
	v_mfma_f32_16x16x32_bf16 v[126:129], v[130:133], v[156:159], v[126:129]
	v_mfma_f32_16x16x32_bf16 v[122:125], v[138:141], v[156:159], v[122:125]
	v_mfma_f32_16x16x32_bf16 v[118:121], v[130:133], v[168:171], v[118:121]
	v_mfma_f32_16x16x32_bf16 v[114:117], v[138:141], v[168:171], v[114:117]
	v_mfma_f32_16x16x32_bf16 v[110:113], v[130:133], v[180:183], v[110:113]
	v_mfma_f32_16x16x32_bf16 v[94:97], v[138:141], v[180:183], v[94:97]
	v_mfma_f32_16x16x32_bf16 v[86:89], v[130:133], v[188:191], v[86:89]
	v_mfma_f32_16x16x32_bf16 v[78:81], v[138:141], v[188:191], v[78:81]
	v_mfma_f32_16x16x32_bf16 v[126:129], v[134:137], v[164:167], v[126:129]
	v_mfma_f32_16x16x32_bf16 v[122:125], v[142:145], v[164:167], v[122:125]
	v_mfma_f32_16x16x32_bf16 v[118:121], v[134:137], v[172:175], v[118:121]
	v_mfma_f32_16x16x32_bf16 v[114:117], v[142:145], v[172:175], v[114:117]
	v_mfma_f32_16x16x32_bf16 v[110:113], v[134:137], v[184:187], v[110:113]
	v_mfma_f32_16x16x32_bf16 v[94:97], v[142:145], v[184:187], v[94:97]
	v_mfma_f32_16x16x32_bf16 v[86:89], v[134:137], v[192:195], v[86:89]
	v_mfma_f32_16x16x32_bf16 v[78:81], v[142:145], v[192:195], v[78:81]
	v_mfma_f32_16x16x32_bf16 v[106:109], v[196:199], v[156:159], v[106:109]
	v_mfma_f32_16x16x32_bf16 v[102:105], v[204:207], v[156:159], v[102:105]
	v_mfma_f32_16x16x32_bf16 v[98:101], v[196:199], v[168:171], v[98:101]
	v_mfma_f32_16x16x32_bf16 v[90:93], v[204:207], v[168:171], v[90:93]
	v_mfma_f32_16x16x32_bf16 v[82:85], v[196:199], v[180:183], v[82:85]
	v_mfma_f32_16x16x32_bf16 v[74:77], v[204:207], v[180:183], v[74:77]
	v_mfma_f32_16x16x32_bf16 v[70:73], v[196:199], v[188:191], v[70:73]
	v_mfma_f32_16x16x32_bf16 v[66:69], v[204:207], v[188:191], v[66:69]
	v_mfma_f32_16x16x32_bf16 v[106:109], v[200:203], v[164:167], v[106:109]
	v_mfma_f32_16x16x32_bf16 v[102:105], v[208:211], v[164:167], v[102:105]
	v_mfma_f32_16x16x32_bf16 v[98:101], v[200:203], v[172:175], v[98:101]
	v_mfma_f32_16x16x32_bf16 v[90:93], v[208:211], v[172:175], v[90:93]
	v_mfma_f32_16x16x32_bf16 v[82:85], v[200:203], v[184:187], v[82:85]
	v_mfma_f32_16x16x32_bf16 v[74:77], v[208:211], v[184:187], v[74:77]
	v_mfma_f32_16x16x32_bf16 v[70:73], v[200:203], v[192:195], v[70:73]
	v_mfma_f32_16x16x32_bf16 v[66:69], v[208:211], v[192:195], v[66:69]
	s_setprio 0
	s_barrier
	ds_read_b128 v[156:159], v163 offset:16384
	ds_read_b128 v[164:167], v163 offset:17408
	ds_read_b128 v[168:171], v163 offset:18432
	ds_read_b128 v[172:175], v163 offset:19456
	ds_read_b128 v[180:183], v163 offset:20480
	ds_read_b128 v[184:187], v163 offset:21504
	ds_read_b128 v[188:191], v163 offset:22528
	ds_read_b128 v[192:195], v163 offset:23552
	s_add_i32 m0, s21, 0x10000
	s_nop 0
	global_load_lds_dwordx4 v32, s[16:17]
	s_add_i32 m0, s21, 0x12000
	s_nop 0
	global_load_lds_dwordx4 v146, s[16:17]
	s_mov_b32 m0, s24
	s_nop 0
	global_load_lds_dwordx4 v150, s[18:19]
	s_mov_b32 m0, s25
	s_nop 0
	global_load_lds_dwordx4 v148, s[18:19]
	s_add_u32 s40, s16, 0x80000
	s_addc_u32 s41, s17, 0
	s_add_i32 m0, s21, 0x14000
	s_nop 0
	global_load_lds_dwordx4 v32, s[40:41]
	s_add_i32 m0, s21, 0x16000
	s_nop 0
	global_load_lds_dwordx4 v146, s[40:41]
	s_waitcnt vmcnt(6)
	s_waitcnt lgkmcnt(0)
	s_barrier
	s_setprio 1
	v_mfma_f32_16x16x32_bf16 v[62:65], v[130:133], v[156:159], v[62:65]
	v_mfma_f32_16x16x32_bf16 v[58:61], v[138:141], v[156:159], v[58:61]
	v_mfma_f32_16x16x32_bf16 v[54:57], v[130:133], v[168:171], v[54:57]
	v_mfma_f32_16x16x32_bf16 v[50:53], v[138:141], v[168:171], v[50:53]
	v_mfma_f32_16x16x32_bf16 v[38:41], v[130:133], v[180:183], v[38:41]
	v_mfma_f32_16x16x32_bf16 v[28:31], v[138:141], v[180:183], v[28:31]
	v_mfma_f32_16x16x32_bf16 v[20:23], v[130:133], v[188:191], v[20:23]
	v_mfma_f32_16x16x32_bf16 v[12:15], v[138:141], v[188:191], v[12:15]
	v_mfma_f32_16x16x32_bf16 v[62:65], v[134:137], v[164:167], v[62:65]
	v_mfma_f32_16x16x32_bf16 v[58:61], v[142:145], v[164:167], v[58:61]
	v_mfma_f32_16x16x32_bf16 v[54:57], v[134:137], v[172:175], v[54:57]
	v_mfma_f32_16x16x32_bf16 v[50:53], v[142:145], v[172:175], v[50:53]
	v_mfma_f32_16x16x32_bf16 v[38:41], v[134:137], v[184:187], v[38:41]
	v_mfma_f32_16x16x32_bf16 v[28:31], v[142:145], v[184:187], v[28:31]
	v_mfma_f32_16x16x32_bf16 v[20:23], v[134:137], v[192:195], v[20:23]
	v_mfma_f32_16x16x32_bf16 v[12:15], v[142:145], v[192:195], v[12:15]
	v_mfma_f32_16x16x32_bf16 v[46:49], v[196:199], v[156:159], v[46:49]
	v_mfma_f32_16x16x32_bf16 v[42:45], v[204:207], v[156:159], v[42:45]
	v_mfma_f32_16x16x32_bf16 v[34:37], v[196:199], v[168:171], v[34:37]
	v_mfma_f32_16x16x32_bf16 v[24:27], v[204:207], v[168:171], v[24:27]
	v_mfma_f32_16x16x32_bf16 v[16:19], v[196:199], v[180:183], v[16:19]
	v_mfma_f32_16x16x32_bf16 v[8:11], v[204:207], v[180:183], v[8:11]
	v_mfma_f32_16x16x32_bf16 v[4:7], v[196:199], v[188:191], v[4:7]
	v_mfma_f32_16x16x32_bf16 v[0:3], v[204:207], v[188:191], v[0:3]
	v_mfma_f32_16x16x32_bf16 v[46:49], v[200:203], v[164:167], v[46:49]
	v_mfma_f32_16x16x32_bf16 v[42:45], v[208:211], v[164:167], v[42:45]
	v_mfma_f32_16x16x32_bf16 v[34:37], v[200:203], v[172:175], v[34:37]
	v_mfma_f32_16x16x32_bf16 v[24:27], v[208:211], v[172:175], v[24:27]
	v_mfma_f32_16x16x32_bf16 v[16:19], v[200:203], v[184:187], v[16:19]
	v_mfma_f32_16x16x32_bf16 v[8:11], v[208:211], v[184:187], v[8:11]
	v_mfma_f32_16x16x32_bf16 v[4:7], v[200:203], v[192:195], v[4:7]
	v_mfma_f32_16x16x32_bf16 v[0:3], v[208:211], v[192:195], v[0:3]
	s_setprio 0
	s_add_i32 s40, 0, 0x18000
	v_add_u32_e32 v142, s40, v161
	s_barrier
	ds_read_b128 v[130:133], v142
	ds_read_b128 v[134:137], v142 offset:1024
	ds_read_b128 v[138:141], v142 offset:2048
	ds_read_b128 v[142:145], v142 offset:3072
	s_add_u32 s18, s18, 0x80000
	s_addc_u32 s19, s19, 0
	s_add_i32 s40, 0, 0x1c000
	v_add_u32_e32 v208, s40, v161
	ds_read_b128 v[196:199], v208
	ds_read_b128 v[200:203], v208 offset:1024
	ds_read_b128 v[204:207], v208 offset:2048
	ds_read_b128 v[208:211], v208 offset:3072
	s_mov_b32 m0, s26
	s_nop 0
	global_load_lds_dwordx4 v150, s[18:19]
	ds_read_b128 v[156:159], v163 offset:32768
	ds_read_b128 v[164:167], v163 offset:33792
	ds_read_b128 v[168:171], v163 offset:34816
	ds_read_b128 v[172:175], v163 offset:35840
	ds_read_b128 v[180:183], v163 offset:36864
	ds_read_b128 v[184:187], v163 offset:37888
	ds_read_b128 v[188:191], v163 offset:38912
	ds_read_b128 v[192:195], v163 offset:39936
	s_mov_b32 m0, s27
	s_nop 0
	global_load_lds_dwordx4 v148, s[18:19]
	s_waitcnt lgkmcnt(0)
	s_barrier
	s_setprio 1
	v_mfma_f32_16x16x32_bf16 v[126:129], v[130:133], v[156:159], v[126:129]
	v_mfma_f32_16x16x32_bf16 v[122:125], v[138:141], v[156:159], v[122:125]
	v_mfma_f32_16x16x32_bf16 v[118:121], v[130:133], v[168:171], v[118:121]
	v_mfma_f32_16x16x32_bf16 v[114:117], v[138:141], v[168:171], v[114:117]
	v_mfma_f32_16x16x32_bf16 v[110:113], v[130:133], v[180:183], v[110:113]
	v_mfma_f32_16x16x32_bf16 v[94:97], v[138:141], v[180:183], v[94:97]
	v_mfma_f32_16x16x32_bf16 v[86:89], v[130:133], v[188:191], v[86:89]
	v_mfma_f32_16x16x32_bf16 v[78:81], v[138:141], v[188:191], v[78:81]
	v_mfma_f32_16x16x32_bf16 v[126:129], v[134:137], v[164:167], v[126:129]
	v_mfma_f32_16x16x32_bf16 v[122:125], v[142:145], v[164:167], v[122:125]
	v_mfma_f32_16x16x32_bf16 v[118:121], v[134:137], v[172:175], v[118:121]
	v_mfma_f32_16x16x32_bf16 v[114:117], v[142:145], v[172:175], v[114:117]
	v_mfma_f32_16x16x32_bf16 v[110:113], v[134:137], v[184:187], v[110:113]
	v_mfma_f32_16x16x32_bf16 v[94:97], v[142:145], v[184:187], v[94:97]
	v_mfma_f32_16x16x32_bf16 v[86:89], v[134:137], v[192:195], v[86:89]
	v_mfma_f32_16x16x32_bf16 v[78:81], v[142:145], v[192:195], v[78:81]
	v_mfma_f32_16x16x32_bf16 v[106:109], v[196:199], v[156:159], v[106:109]
	v_mfma_f32_16x16x32_bf16 v[102:105], v[204:207], v[156:159], v[102:105]
	v_mfma_f32_16x16x32_bf16 v[98:101], v[196:199], v[168:171], v[98:101]
	v_mfma_f32_16x16x32_bf16 v[90:93], v[204:207], v[168:171], v[90:93]
	v_mfma_f32_16x16x32_bf16 v[82:85], v[196:199], v[180:183], v[82:85]
	v_mfma_f32_16x16x32_bf16 v[74:77], v[204:207], v[180:183], v[74:77]
	v_mfma_f32_16x16x32_bf16 v[70:73], v[196:199], v[188:191], v[70:73]
	v_mfma_f32_16x16x32_bf16 v[66:69], v[204:207], v[188:191], v[66:69]
	v_mfma_f32_16x16x32_bf16 v[106:109], v[200:203], v[164:167], v[106:109]
	v_mfma_f32_16x16x32_bf16 v[102:105], v[208:211], v[164:167], v[102:105]
	v_mfma_f32_16x16x32_bf16 v[98:101], v[200:203], v[172:175], v[98:101]
	v_mfma_f32_16x16x32_bf16 v[90:93], v[208:211], v[172:175], v[90:93]
	v_mfma_f32_16x16x32_bf16 v[82:85], v[200:203], v[184:187], v[82:85]
	v_mfma_f32_16x16x32_bf16 v[74:77], v[208:211], v[184:187], v[74:77]
	v_mfma_f32_16x16x32_bf16 v[70:73], v[200:203], v[192:195], v[70:73]
	v_mfma_f32_16x16x32_bf16 v[66:69], v[208:211], v[192:195], v[66:69]
	s_setprio 0
	s_barrier
	ds_read_b128 v[156:159], v163 offset:49152
	ds_read_b128 v[164:167], v163 offset:50176
	ds_read_b128 v[168:171], v163 offset:51200
	ds_read_b128 v[172:175], v163 offset:52224
	ds_read_b128 v[180:183], v163 offset:53248
	ds_read_b128 v[184:187], v163 offset:54272
	ds_read_b128 v[188:191], v163 offset:55296
	ds_read_b128 v[192:195], v163 offset:56320
	s_add_u32 s16, s16, 0x80
	s_addc_u32 s17, s17, 0
	s_add_i32 m0, s21, 0x18000
	s_nop 0
	global_load_lds_dwordx4 v32, s[16:17]
	s_add_i32 m0, s21, 0x1a000
	s_nop 0
	global_load_lds_dwordx4 v146, s[16:17]
	s_add_u32 s18, s18, 0xfff80080
	s_addc_u32 s19, s19, -1
	s_mov_b32 m0, s34
	s_nop 0
	global_load_lds_dwordx4 v150, s[18:19]
	s_mov_b32 m0, s35
	s_nop 0
	global_load_lds_dwordx4 v148, s[18:19]
	s_add_u32 s16, s16, 0x80000
	s_addc_u32 s17, s17, 0
	s_add_i32 m0, s21, 0x1c000
	s_nop 0
	global_load_lds_dwordx4 v32, s[16:17]
	s_add_i32 m0, s21, 0x1e000
	s_nop 0
	global_load_lds_dwordx4 v146, s[16:17]
	s_waitcnt vmcnt(6)
	s_waitcnt lgkmcnt(0)
	s_barrier
	s_setprio 1
	v_mfma_f32_16x16x32_bf16 v[62:65], v[130:133], v[156:159], v[62:65]
	v_mfma_f32_16x16x32_bf16 v[58:61], v[138:141], v[156:159], v[58:61]
	v_mfma_f32_16x16x32_bf16 v[54:57], v[130:133], v[168:171], v[54:57]
	v_mfma_f32_16x16x32_bf16 v[50:53], v[138:141], v[168:171], v[50:53]
	v_mfma_f32_16x16x32_bf16 v[38:41], v[130:133], v[180:183], v[38:41]
	v_mfma_f32_16x16x32_bf16 v[28:31], v[138:141], v[180:183], v[28:31]
	v_mfma_f32_16x16x32_bf16 v[20:23], v[130:133], v[188:191], v[20:23]
	v_mfma_f32_16x16x32_bf16 v[12:15], v[138:141], v[188:191], v[12:15]
	v_mfma_f32_16x16x32_bf16 v[62:65], v[134:137], v[164:167], v[62:65]
	v_mfma_f32_16x16x32_bf16 v[58:61], v[142:145], v[164:167], v[58:61]
	v_mfma_f32_16x16x32_bf16 v[54:57], v[134:137], v[172:175], v[54:57]
	v_mfma_f32_16x16x32_bf16 v[50:53], v[142:145], v[172:175], v[50:53]
	v_mfma_f32_16x16x32_bf16 v[38:41], v[134:137], v[184:187], v[38:41]
	v_mfma_f32_16x16x32_bf16 v[28:31], v[142:145], v[184:187], v[28:31]
	v_mfma_f32_16x16x32_bf16 v[20:23], v[134:137], v[192:195], v[20:23]
	v_mfma_f32_16x16x32_bf16 v[12:15], v[142:145], v[192:195], v[12:15]
	v_mfma_f32_16x16x32_bf16 v[46:49], v[196:199], v[156:159], v[46:49]
	v_mfma_f32_16x16x32_bf16 v[42:45], v[204:207], v[156:159], v[42:45]
	v_mfma_f32_16x16x32_bf16 v[34:37], v[196:199], v[168:171], v[34:37]
	v_mfma_f32_16x16x32_bf16 v[24:27], v[204:207], v[168:171], v[24:27]
	v_mfma_f32_16x16x32_bf16 v[16:19], v[196:199], v[180:183], v[16:19]
	v_mfma_f32_16x16x32_bf16 v[8:11], v[204:207], v[180:183], v[8:11]
	v_mfma_f32_16x16x32_bf16 v[4:7], v[196:199], v[188:191], v[4:7]
	v_mfma_f32_16x16x32_bf16 v[0:3], v[204:207], v[188:191], v[0:3]
	v_mfma_f32_16x16x32_bf16 v[46:49], v[200:203], v[164:167], v[46:49]
	v_mfma_f32_16x16x32_bf16 v[42:45], v[208:211], v[164:167], v[42:45]
	v_mfma_f32_16x16x32_bf16 v[34:37], v[200:203], v[172:175], v[34:37]
	v_mfma_f32_16x16x32_bf16 v[24:27], v[208:211], v[172:175], v[24:27]
	v_mfma_f32_16x16x32_bf16 v[16:19], v[200:203], v[184:187], v[16:19]
	v_mfma_f32_16x16x32_bf16 v[8:11], v[208:211], v[184:187], v[8:11]
	v_mfma_f32_16x16x32_bf16 v[4:7], v[200:203], v[192:195], v[4:7]
	v_mfma_f32_16x16x32_bf16 v[0:3], v[208:211], v[192:195], v[0:3]
	s_setprio 0
	s_add_i32 s39, s39, 2
	s_add_u32 s14, s14, 0x100
	s_addc_u32 s15, s15, 0
	s_add_u32 s11, s11, 0x100
	s_addc_u32 s13, s13, 0
	s_cmp_gt_u32 s39, 29
	s_barrier
	s_cbranch_scc0 .LBB0_1375
	s_mov_b64 s[14:15], 0
	s_mov_b64 s[18:19], 0
	s_mov_b64 s[16:17], 0
	s_add_u32 s11, s28, s16
	s_addc_u32 s13, s29, s17
	s_ashr_i32 s16, s37, 3
	v_lshl_or_b32 v130, s38, 8, v162
	s_mul_hi_i32 s17, s16, 0x6000
	s_mulk_i32 s16, 0x6000
	s_add_u32 s16, s11, s16
	v_ashrrev_i32_e32 v131, 31, v130
	s_addc_u32 s17, s13, s17
	v_lshlrev_b64 v[156:157], 2, v[130:131]
	v_lshl_add_u32 v158, s37, 8, v160
	v_lshl_add_u64 v[134:135], s[16:17], 0, v[156:157]
	s_add_u32 s16, s31, s14
	v_ashrrev_i32_e32 v159, 31, v158
	s_addc_u32 s17, s30, s15
	v_lshlrev_b64 v[176:177], 13, v[158:159]
	v_lshl_add_u64 v[164:165], s[16:17], 0, v[176:177]
	v_lshl_add_u64 v[178:179], v[164:165], 0, v[156:157]
	global_load_dwordx4 v[138:141], v[134:135], off offset:16
	global_load_dwordx4 v[142:145], v[134:135], off
	global_load_dwordx4 v[130:133], v[134:135], off offset:528
	s_nop 0
	global_load_dwordx4 v[134:137], v[134:135], off offset:512
	s_nop 0
	global_load_dwordx4 v[164:167], v[178:179], off offset:16
	global_load_dwordx4 v[168:171], v[178:179], off
	global_load_dwordx4 v[172:175], v[178:179], off offset:528
	global_load_dwordx4 v[180:183], v[178:179], off offset:512
	v_or_b32_e32 v178, 16, v158
	v_or_b32_e32 v200, 32, v158
	v_ashrrev_i32_e32 v179, 31, v178
	v_ashrrev_i32_e32 v201, 31, v200
	v_lshlrev_b64 v[178:179], 13, v[178:179]
	v_lshlrev_b64 v[224:225], 13, v[200:201]
	v_or_b32_e32 v216, 48, v158
	v_lshl_add_u64 v[184:185], s[16:17], 0, v[178:179]
	v_lshl_add_u64 v[200:201], s[16:17], 0, v[224:225]
	v_ashrrev_i32_e32 v217, 31, v216
	v_lshl_add_u64 v[196:197], v[184:185], 0, v[156:157]
	v_lshl_add_u64 v[212:213], v[200:201], 0, v[156:157]
	v_lshlrev_b64 v[226:227], 13, v[216:217]
	global_load_dwordx4 v[184:187], v[196:197], off offset:16
	global_load_dwordx4 v[188:191], v[196:197], off
	global_load_dwordx4 v[192:195], v[196:197], off offset:528
	s_nop 0
	global_load_dwordx4 v[196:199], v[196:197], off offset:512
	s_nop 0
	global_load_dwordx4 v[200:203], v[212:213], off
	global_load_dwordx4 v[204:207], v[212:213], off offset:16
	global_load_dwordx4 v[208:211], v[212:213], off offset:512
	s_nop 0
	global_load_dwordx4 v[212:215], v[212:213], off offset:528
	v_lshl_add_u64 v[216:217], s[16:17], 0, v[226:227]
	v_lshl_add_u64 v[228:229], v[216:217], 0, v[156:157]
	global_load_dwordx4 v[216:219], v[228:229], off
	global_load_dwordx4 v[220:223], v[228:229], off offset:16
	global_load_dwordx4 v[236:239], v[228:229], off offset:512
	global_load_dwordx4 v[240:243], v[228:229], off offset:528
	s_add_u32 s14, s8, s18
	s_addc_u32 s15, s9, s19
	v_lshl_add_u64 v[176:177], s[14:15], 0, v[176:177]
	v_lshl_add_u64 v[224:225], s[14:15], 0, v[224:225]
	v_lshl_add_u64 v[178:179], s[14:15], 0, v[178:179]
	v_lshl_add_u64 v[176:177], v[176:177], 0, v[156:157]
	v_lshl_add_u64 v[224:225], v[224:225], 0, v[156:157]
	v_lshl_add_u64 v[178:179], v[178:179], 0, v[156:157]
	s_and_b64 vcc, exec, s[2:3]
	s_mov_b32 s38, s12
	s_mov_b32 s37, s10
	s_waitcnt vmcnt(0)
	v_pk_fma_f32 v[124:125], v[124:125], v[140:141], v[166:167]
	v_pk_fma_f32 v[128:129], v[128:129], v[144:145], v[170:171]
	v_pk_fma_f32 v[126:127], v[126:127], v[142:143], v[168:169]
	v_pk_fma_f32 v[122:123], v[122:123], v[138:139], v[164:165]
	v_pk_fma_f32 v[108:109], v[108:109], v[136:137], v[182:183]
	v_pk_fma_f32 v[106:107], v[106:107], v[134:135], v[180:181]
	v_pk_fma_f32 v[104:105], v[104:105], v[132:133], v[174:175]
	v_pk_fma_f32 v[102:103], v[102:103], v[130:131], v[172:173]
	v_pk_fma_f32 v[116:117], v[116:117], v[140:141], v[186:187]
	v_pk_fma_f32 v[120:121], v[120:121], v[144:145], v[190:191]
	v_pk_fma_f32 v[118:119], v[118:119], v[142:143], v[188:189]
	v_pk_fma_f32 v[84:85], v[84:85], v[136:137], v[210:211]
	v_pk_fma_f32 v[82:83], v[82:83], v[134:135], v[208:209]
	v_pk_fma_f32 v[114:115], v[114:115], v[138:139], v[184:185]
	v_pk_fma_f32 v[100:101], v[100:101], v[136:137], v[198:199]
	v_pk_fma_f32 v[98:99], v[98:99], v[134:135], v[196:197]
	v_pk_fma_f32 v[92:93], v[92:93], v[132:133], v[194:195]
	v_pk_fma_f32 v[90:91], v[90:91], v[130:131], v[192:193]
	v_pk_fma_f32 v[112:113], v[112:113], v[144:145], v[202:203]
	v_pk_fma_f32 v[110:111], v[110:111], v[142:143], v[200:201]
	global_store_dwordx4 v[176:177], v[126:129], off
	global_store_dwordx4 v[176:177], v[122:125], off offset:16
	global_store_dwordx4 v[176:177], v[106:109], off offset:512
	global_store_dwordx4 v[176:177], v[102:105], off offset:528
	global_store_dwordx4 v[178:179], v[118:121], off
	global_store_dwordx4 v[178:179], v[114:117], off offset:16
	global_store_dwordx4 v[178:179], v[98:101], off offset:512
	global_store_dwordx4 v[178:179], v[90:93], off offset:528
	global_store_dwordx4 v[224:225], v[110:113], off
	global_store_dwordx4 v[224:225], v[82:85], off offset:512
	v_pk_fma_f32 v[76:77], v[76:77], v[132:133], v[214:215]
	v_pk_fma_f32 v[74:75], v[74:75], v[130:131], v[212:213]
	v_lshl_add_u64 v[82:83], s[14:15], 0, v[226:227]
	global_store_dwordx4 v[224:225], v[74:77], off offset:528
	v_lshl_add_u64 v[82:83], v[82:83], 0, v[156:157]
	v_pk_fma_f32 v[72:73], v[72:73], v[136:137], v[238:239]
	v_pk_fma_f32 v[76:77], v[88:89], v[144:145], v[218:219]
	v_pk_fma_f32 v[74:75], v[86:87], v[142:143], v[216:217]
	global_store_dwordx4 v[82:83], v[74:77], off
	v_pk_fma_f32 v[70:71], v[70:71], v[134:135], v[236:237]
	v_pk_fma_f32 v[68:69], v[68:69], v[132:133], v[242:243]
	v_pk_fma_f32 v[76:77], v[80:81], v[140:141], v[222:223]
	v_pk_fma_f32 v[74:75], v[78:79], v[138:139], v[220:221]
	v_pk_fma_f32 v[66:67], v[66:67], v[130:131], v[240:241]
	global_store_dwordx4 v[82:83], v[74:77], off offset:16
	global_store_dwordx4 v[82:83], v[70:73], off offset:512
	global_store_dwordx4 v[82:83], v[66:69], off offset:528
	v_add_u32_e32 v82, 0x90, v158
	v_ashrrev_i32_e32 v83, 31, v82
	v_add_u32_e32 v66, 0x80, v158
	v_ashrrev_i32_e32 v67, 31, v66
	v_lshlrev_b64 v[164:165], 13, v[66:67]
	v_lshlrev_b64 v[166:167], 13, v[82:83]
	v_add_u32_e32 v98, 0xa0, v158
	v_pk_fma_f32 v[92:93], v[96:97], v[140:141], v[206:207]
	v_pk_fma_f32 v[90:91], v[94:95], v[138:139], v[204:205]
	v_lshl_add_u64 v[66:67], s[16:17], 0, v[164:165]
	v_lshl_add_u64 v[82:83], s[16:17], 0, v[166:167]
	v_ashrrev_i32_e32 v99, 31, v98
	global_store_dwordx4 v[224:225], v[90:93], off offset:16
	v_lshl_add_u64 v[78:79], v[66:67], 0, v[156:157]
	v_lshl_add_u64 v[94:95], v[82:83], 0, v[156:157]
	v_lshlrev_b64 v[168:169], 13, v[98:99]
	v_add_u32_e32 v114, 0xb0, v158
	global_load_dwordx4 v[66:69], v[78:79], off offset:16
	global_load_dwordx4 v[70:73], v[78:79], off
	global_load_dwordx4 v[74:77], v[78:79], off offset:528
	s_nop 0
	global_load_dwordx4 v[78:81], v[78:79], off offset:512
	s_nop 0
	global_load_dwordx4 v[82:85], v[94:95], off
	global_load_dwordx4 v[86:89], v[94:95], off offset:16
	global_load_dwordx4 v[90:93], v[94:95], off offset:512
	s_nop 0
	global_load_dwordx4 v[94:97], v[94:95], off offset:528
	v_lshl_add_u64 v[98:99], s[16:17], 0, v[168:169]
	v_ashrrev_i32_e32 v115, 31, v114
	v_lshl_add_u64 v[110:111], v[98:99], 0, v[156:157]
	v_lshlrev_b64 v[158:159], 13, v[114:115]
	global_load_dwordx4 v[98:101], v[110:111], off
	global_load_dwordx4 v[102:105], v[110:111], off offset:16
	global_load_dwordx4 v[106:109], v[110:111], off offset:512
	s_nop 0
	global_load_dwordx4 v[110:113], v[110:111], off offset:528
	v_lshl_add_u64 v[114:115], s[16:17], 0, v[158:159]
	v_lshl_add_u64 v[126:127], v[114:115], 0, v[156:157]
	global_load_dwordx4 v[114:117], v[126:127], off
	global_load_dwordx4 v[118:121], v[126:127], off offset:16
	global_load_dwordx4 v[122:125], v[126:127], off offset:512
	s_nop 0
	global_load_dwordx4 v[126:129], v[126:127], off offset:528
	v_lshl_add_u64 v[164:165], s[14:15], 0, v[164:165]
	v_lshl_add_u64 v[166:167], s[14:15], 0, v[166:167]
	v_lshl_add_u64 v[164:165], v[164:165], 0, v[156:157]
	v_lshl_add_u64 v[166:167], v[166:167], 0, v[156:157]
	s_mov_b64 s[16:17], s[6:7]
	s_waitcnt vmcnt(0)
	v_pk_fma_f32 v[60:61], v[60:61], v[140:141], v[68:69]
	v_pk_fma_f32 v[64:65], v[64:65], v[144:145], v[72:73]
	v_pk_fma_f32 v[62:63], v[62:63], v[142:143], v[70:71]
	v_pk_fma_f32 v[36:37], v[36:37], v[136:137], v[92:93]
	v_pk_fma_f32 v[34:35], v[34:35], v[134:135], v[90:91]
	v_pk_fma_f32 v[58:59], v[58:59], v[138:139], v[66:67]
	v_pk_fma_f32 v[48:49], v[48:49], v[136:137], v[80:81]
	v_pk_fma_f32 v[46:47], v[46:47], v[134:135], v[78:79]
	v_pk_fma_f32 v[44:45], v[44:45], v[132:133], v[76:77]
	v_pk_fma_f32 v[42:43], v[42:43], v[130:131], v[74:75]
	v_pk_fma_f32 v[56:57], v[56:57], v[144:145], v[84:85]
	v_pk_fma_f32 v[54:55], v[54:55], v[142:143], v[82:83]
	v_pk_fma_f32 v[52:53], v[52:53], v[140:141], v[88:89]
	v_pk_fma_f32 v[50:51], v[50:51], v[138:139], v[86:87]
	global_store_dwordx4 v[164:165], v[62:65], off
	global_store_dwordx4 v[164:165], v[58:61], off offset:16
	global_store_dwordx4 v[164:165], v[46:49], off offset:512
	global_store_dwordx4 v[164:165], v[42:45], off offset:528
	global_store_dwordx4 v[166:167], v[54:57], off
	global_store_dwordx4 v[166:167], v[50:53], off offset:16
	global_store_dwordx4 v[166:167], v[34:37], off offset:512
	v_pk_fma_f32 v[18:19], v[18:19], v[136:137], v[108:109]
	v_pk_fma_f32 v[16:17], v[16:17], v[134:135], v[106:107]
	v_lshl_add_u64 v[34:35], s[14:15], 0, v[168:169]
	v_lshl_add_u64 v[34:35], v[34:35], 0, v[156:157]
	v_pk_fma_f32 v[26:27], v[26:27], v[132:133], v[96:97]
	v_pk_fma_f32 v[24:25], v[24:25], v[130:131], v[94:95]
	global_store_dwordx4 v[34:35], v[16:19], off offset:512
	v_pk_fma_f32 v[10:11], v[10:11], v[132:133], v[112:113]
	v_pk_fma_f32 v[8:9], v[8:9], v[130:131], v[110:111]
	v_lshl_add_u64 v[16:17], s[14:15], 0, v[158:159]
	global_store_dwordx4 v[166:167], v[24:27], off offset:528
	global_store_dwordx4 v[34:35], v[8:11], off offset:528
	v_lshl_add_u64 v[16:17], v[16:17], 0, v[156:157]
	v_pk_fma_f32 v[26:27], v[40:41], v[144:145], v[100:101]
	v_pk_fma_f32 v[24:25], v[38:39], v[142:143], v[98:99]
	v_pk_fma_f32 v[10:11], v[22:23], v[144:145], v[116:117]
	v_pk_fma_f32 v[8:9], v[20:21], v[142:143], v[114:115]
	global_store_dwordx4 v[34:35], v[24:27], off
	global_store_dwordx4 v[16:17], v[8:11], off
	v_pk_fma_f32 v[6:7], v[6:7], v[136:137], v[124:125]
	v_pk_fma_f32 v[26:27], v[30:31], v[140:141], v[104:105]
	v_pk_fma_f32 v[24:25], v[28:29], v[138:139], v[102:103]
	v_pk_fma_f32 v[10:11], v[14:15], v[140:141], v[120:121]
	v_pk_fma_f32 v[8:9], v[12:13], v[138:139], v[118:119]
	v_pk_fma_f32 v[4:5], v[4:5], v[134:135], v[122:123]
	v_pk_fma_f32 v[2:3], v[2:3], v[132:133], v[128:129]
	v_pk_fma_f32 v[0:1], v[0:1], v[130:131], v[126:127]
	s_mov_b64 s[14:15], s[4:5]
	global_store_dwordx4 v[34:35], v[24:27], off offset:16
	global_store_dwordx4 v[16:17], v[8:11], off offset:16
	global_store_dwordx4 v[16:17], v[4:7], off offset:512
	global_store_dwordx4 v[16:17], v[0:3], off offset:528
	s_cbranch_vccz .LBB0_1364
	s_waitcnt vmcnt(0)
	s_cmpk_gt_u32 s20, 0xff
	s_cbranch_scc1 .LBB0_1379
	s_barrier
